# attention loop: one counted LDS wait per two MFMAs (12 fewer instructions per tile step)
# speedup vs baseline: 1.0056x; 1.0056x over previous
.LBB0_456:
	s_mov_b32 s99, s98
	s_lshl_b32 s80, s10, 14
	v_add_u32_e32 v179, s80, v219
	v_add_u32_e32 v126, v179, v149
	ds_read_b128 v[102:105], v126 offset:49152
	ds_read_b128 v[118:121], v126 offset:53248
	ds_read_b128 v[122:125], v126 offset:57344
	ds_read_b128 v[228:231], v126 offset:61440
	s_add_i32 s78, s34, -1
	s_add_i32 s63, s60, 0x80
	s_lshl_b32 s79, s62, 14
	s_cmp_le_i32 s78, s48
	s_cselect_b64 s[4:5], -1, 0
	s_cmp_gt_i32 s78, s48
	s_waitcnt lgkmcnt(2)
	v_mfma_f32_32x32x16_bf16 v[50:65], v[102:105], v[98:101], v[50:65]
	v_exp_f32_e32 v66, v66
	v_exp_f32_e32 v249, v82
	v_add_u32_e32 v181, v179, v208
	ds_read_b128 v[102:105], v181 offset:49152
	v_mfma_f32_32x32x16_bf16 v[34:49], v[118:121], v[98:101], v[34:49]
	v_add_f32_e32 v254, 0, v66
	v_add_f32_e32 v254, v249, v254
	v_exp_f32_e32 v67, v67
	v_exp_f32_e32 v250, v83
	ds_read_b128 v[232:235], v181 offset:53248
	s_waitcnt lgkmcnt(2)
	v_mfma_f32_32x32x16_bf16 v[18:33], v[122:125], v[98:101], v[18:33]
	v_add_f32_e32 v254, v67, v254
	v_add_f32_e32 v254, v250, v254
	v_exp_f32_e32 v68, v68
	v_exp_f32_e32 v195, v84
	ds_read_b128 v[126:129], v181 offset:57344
	v_mfma_f32_32x32x16_bf16 v[2:17], v[228:231], v[98:101], v[2:17]
	v_add_f32_e32 v254, v68, v254
	v_add_f32_e32 v254, v195, v254
	v_exp_f32_e32 v69, v69
	v_exp_f32_e32 v251, v85
	ds_read_b128 v[118:121], v181 offset:61440
	s_waitcnt lgkmcnt(2)
	v_mfma_f32_32x32x16_bf16 v[50:65], v[102:105], v[106:109], v[50:65]
	v_add_f32_e32 v254, v69, v254
	v_add_f32_e32 v254, v251, v254
	v_exp_f32_e32 v70, v70
	v_exp_f32_e32 v252, v86
	v_add_u32_e32 v181, v179, v209
	ds_read_b128 v[122:125], v181 offset:49152
	v_mfma_f32_32x32x16_bf16 v[34:49], v[232:235], v[106:109], v[34:49]
	s_cbranch_scc1 .LBB0_458
	s_add_i32 s78, s34, -3
	s_add_i32 s81, s60, 0x100
	s_cmp_lt_i32 s78, s39
	s_cselect_b32 s82, s63, s81
	s_ashr_i32 s83, s82, 31
	s_lshl_b64 s[82:83], s[82:83], 12
	s_add_i32 s78, s79, 0xffffc000
	s_cmp_lg_u32 s62, 0
	s_cselect_b32 s78, s78, 0x8000
	v_lshl_add_u64 v[98:99], v[202:203], 0, s[82:83]
	s_add_i32 s78, s7, s78
	v_lshl_add_u64 v[100:101], v[98:99], 0, s[30:31]
	s_mov_b32 m0, s78
	v_lshl_add_u64 v[98:99], v[98:99], 0, s[36:37]
	global_load_lds_dwordx4 v[100:101], off
	s_add_i32 m0, s78, 0x2000
	s_nop 0
	global_load_lds_dwordx4 v[98:99], off
.LBB0_458:
	s_add_i32 s78, s34, -4
	s_cmp_gt_i32 s78, s39
	s_cselect_b64 s[82:83], -1, 0
	v_cndmask_b32_e64 v200, v201, -v201, s[82:83]
	s_and_b64 s[82:83], s[82:83], exec
	s_cselect_b32 s82, s63, s60
	s_ashr_i32 s83, s82, 31
	s_lshl_b64 s[84:85], s[82:83], 1
	s_addk_i32 s80, 0xc000
	s_cmp_lg_u32 s10, 0
	s_cselect_b32 s80, s80, 0x8000
	s_add_i32 s80, s14, s80
	v_lshl_add_u64 v[98:99], v[204:205], 0, s[84:85]
	s_add_i32 m0, s80, 0xc000
	v_lshl_add_u64 v[100:101], v[206:207], 0, s[84:85]
	global_load_lds_dwordx4 v[98:99], off
	s_add_i32 m0, s80, 0xc400
	v_cvt_f32_i32_e32 v98, s82
	global_load_lds_dwordx4 v[100:101], off
	v_add_u32_e32 v183, s79, v218
	v_add_f32_e32 v98, v155, v98
	v_fma_f32 v224, v200, v98, -v199
	v_fma_f32 v98, 0, v200, v224
	v_add_f32_e32 v99, v200, v224
	v_fma_f32 v100, v200, s64, v224
	v_fma_f32 v101, v200, s65, v224
	v_fma_f32 v102, v200, s66, v224
	v_fma_f32 v103, v200, s67, v224
	v_mul_f32_e32 v240, 0x42000000, v200
	ds_read_b128 v[228:231], v181 offset:53248
	s_waitcnt lgkmcnt(2)
	v_mfma_f32_32x32x16_bf16 v[18:33], v[126:129], v[106:109], v[18:33]
	v_add_f32_e32 v254, v70, v254
	v_add_f32_e32 v254, v252, v254
	v_exp_f32_e32 v71, v71
	v_fma_f32 v104, v200, s68, v224
	v_fma_f32 v105, v200, s69, v224
	ds_read_b128 v[126:129], v181 offset:57344
	v_mfma_f32_32x32x16_bf16 v[2:17], v[118:121], v[106:109], v[2:17]
	s_setprio 0
	v_add_f32_e32 v254, v71, v254
	v_exp_f32_e32 v253, v87
	v_exp_f32_e32 v82, v72
	ds_read_b128 v[118:121], v181 offset:61440
	s_waitcnt lgkmcnt(2)
	v_mfma_f32_32x32x16_bf16 v[50:65], v[122:125], v[110:113], v[50:65]
	v_add_f32_e32 v254, v253, v254
	v_add_f32_e32 v254, v82, v254
	v_exp_f32_e32 v72, v88
	v_fma_f32 v106, v200, s70, v224
	v_fma_f32 v107, v200, s71, v224
	v_add_u32_e32 v179, v179, v226
	ds_read_b128 v[122:125], v179 offset:49152
	v_mfma_f32_32x32x16_bf16 v[34:49], v[228:231], v[110:113], v[34:49]
	v_add_f32_e32 v254, v72, v254
	v_exp_f32_e32 v83, v73
	v_exp_f32_e32 v73, v89
	ds_read_b128 v[228:231], v179 offset:53248
	s_waitcnt lgkmcnt(2)
	v_mfma_f32_32x32x16_bf16 v[18:33], v[126:129], v[110:113], v[18:33]
	v_add_f32_e32 v254, v83, v254
	v_add_f32_e32 v254, v73, v254
	v_exp_f32_e32 v74, v74
	v_fma_f32 v108, v200, s72, v224
	v_fma_f32 v109, v200, s73, v224
	ds_read_b128 v[126:129], v179 offset:57344
	v_mfma_f32_32x32x16_bf16 v[2:17], v[118:121], v[110:113], v[2:17]
	v_add_f32_e32 v254, v74, v254
	v_exp_f32_e32 v90, v90
	v_exp_f32_e32 v75, v75
	ds_read_b128 v[118:121], v179 offset:61440
	s_waitcnt lgkmcnt(2)
	v_mfma_f32_32x32x16_bf16 v[50:65], v[122:125], v[114:117], v[50:65]
	v_add_f32_e32 v254, v90, v254
	v_add_f32_e32 v254, v75, v254
	v_exp_f32_e32 v91, v91
	v_fma_f32 v110, v200, s74, v224
	v_fma_f32 v111, v200, s75, v224
	v_add_u32_e32 v112, v183, v149
	ds_read_b128 v[232:235], v112
	v_mfma_f32_32x32x16_bf16 v[34:49], v[228:231], v[114:117], v[34:49]
	v_add_f32_e32 v254, v91, v254
	v_exp_f32_e32 v76, v76
	v_exp_f32_e32 v92, v92
	ds_read_b128 v[228:231], v112 offset:4096
	s_waitcnt lgkmcnt(2)
	v_mfma_f32_32x32x16_bf16 v[18:33], v[126:129], v[114:117], v[18:33]
	v_add_f32_e32 v254, v76, v254
	v_add_f32_e32 v254, v92, v254
	v_exp_f32_e32 v77, v77
	v_fma_f32 v112, v200, s76, v224
	v_fma_f32 v113, v200, s77, v224
	v_add_u32_e32 v179, v183, v208
	ds_read_b128 v[236:239], v179
	v_mfma_f32_32x32x16_bf16 v[2:17], v[118:121], v[114:117], v[2:17]
	v_add_f32_e64 v114, v240, v98
	v_add_f32_e64 v115, v240, v99
	v_add_f32_e64 v128, v240, v112
	v_add_f32_e64 v129, v240, v113
	v_add_f32_e64 v126, v240, v110
	v_add_f32_e64 v127, v240, v111
	v_add_f32_e32 v124, v240, v108
	v_add_f32_e32 v125, v240, v109
	v_add_f32_e32 v122, v240, v106
	v_add_f32_e32 v123, v240, v107
	v_add_f32_e32 v120, v240, v104
	v_add_f32_e32 v121, v240, v105
	v_add_f32_e32 v118, v240, v102
	v_add_f32_e32 v119, v240, v103
	v_add_f32_e32 v116, v240, v100
	v_add_f32_e32 v117, v240, v101
	ds_read_b128 v[240:243], v179 offset:4096
	s_waitcnt lgkmcnt(2)
	v_mfma_f32_32x32x16_bf16 v[98:113], v[232:235], v[130:133], v[98:113]
	v_add_f32_e32 v254, v77, v254
	v_exp_f32_e32 v93, v93
	v_exp_f32_e32 v78, v78
	v_add_u32_e32 v179, v183, v209
	ds_read_b128 v[232:235], v179
	v_mfma_f32_32x32x16_bf16 v[114:129], v[228:231], v[130:133], v[114:129]
	v_add_f32_e32 v254, v93, v254
	v_add_f32_e32 v254, v78, v254
	v_exp_f32_e32 v94, v94
	v_exp_f32_e32 v79, v79
	ds_read_b128 v[228:231], v179 offset:4096
	s_waitcnt lgkmcnt(2)
	v_mfma_f32_32x32x16_bf16 v[98:113], v[236:239], v[134:137], v[98:113]
	v_add_f32_e32 v254, v94, v254
	v_add_f32_e32 v254, v79, v254
	v_exp_f32_e32 v95, v95
	v_exp_f32_e32 v80, v80
	v_add_u32_e32 v179, v183, v226
	ds_read_b128 v[236:239], v179
	v_mfma_f32_32x32x16_bf16 v[114:129], v[240:243], v[134:137], v[114:129]
	v_add_f32_e32 v254, v95, v254
	v_add_f32_e32 v254, v80, v254
	v_exp_f32_e32 v96, v96
	v_exp_f32_e32 v81, v81
	ds_read_b128 v[240:243], v179 offset:4096
	s_waitcnt lgkmcnt(2)
	v_mfma_f32_32x32x16_bf16 v[98:113], v[232:235], v[138:141], v[98:113]
	v_add_f32_e32 v254, v96, v254
	v_add_f32_e32 v254, v81, v254
	v_exp_f32_e32 v97, v97
	v_mfma_f32_32x32x16_bf16 v[114:129], v[228:231], v[138:141], v[114:129]
	v_add_f32_e32 v254, v97, v254
	s_waitcnt lgkmcnt(0)
	v_mfma_f32_32x32x16_bf16 v[98:113], v[236:239], v[142:145], v[98:113]
	v_mfma_f32_32x32x16_bf16 v[114:129], v[240:243], v[142:145], v[114:129]
	s_andn2_b64 vcc, exec, s[4:5]
	s_mov_b64 s[4:5], -1
	s_cbranch_vccz .LBB0_470
	s_andn2_b64 vcc, exec, s[4:5]
	s_cbranch_vccz .LBB0_471

.LBB0_464:
	s_add_i32 s4, s62, 1
	s_cmp_lg_u32 s62, 2
	s_cselect_b32 s4, s4, 0
	s_add_i32 s5, s10, 1
	s_cmp_lg_u32 s10, 2
	s_cselect_b32 s5, s5, 0
	s_lshl_b32 s62, s5, 14
	v_add_u32_e32 v198, s62, v219
	v_cvt_pk_bf16_f32 v66, v66, v67
	v_cvt_pk_bf16_f32 v67, v68, v69
	v_cvt_pk_bf16_f32 v68, v70, v71
	v_add_u32_e32 v70, v198, v149
	v_cvt_pk_bf16_f32 v69, v82, v83
	v_cvt_pk_bf16_f32 v74, v74, v75
	v_cvt_pk_bf16_f32 v75, v76, v77
	v_cvt_pk_bf16_f32 v76, v78, v79
	v_cvt_pk_bf16_f32 v77, v80, v81
	ds_read_b128 v[78:81], v70 offset:49152
	ds_read_b128 v[82:85], v70 offset:53248
	ds_read_b128 v[86:89], v70 offset:57344
	ds_read_b128 v[228:231], v70 offset:61440
	s_lshl_b32 s10, s4, 14
	s_cmp_gt_i32 s34, s48
	s_waitcnt lgkmcnt(2)
	v_mfma_f32_32x32x16_bf16 v[50:65], v[78:81], v[66:69], v[50:65]
	v_add_u32_e32 v70, v198, v208
	ds_read_b128 v[78:81], v70 offset:49152
	v_mfma_f32_32x32x16_bf16 v[34:49], v[82:85], v[66:69], v[34:49]
	ds_read_b128 v[232:235], v70 offset:53248
	s_waitcnt lgkmcnt(2)
	v_mfma_f32_32x32x16_bf16 v[18:33], v[86:89], v[66:69], v[18:33]
	ds_read_b128 v[86:89], v70 offset:57344
	v_mfma_f32_32x32x16_bf16 v[2:17], v[228:231], v[66:69], v[2:17]
	ds_read_b128 v[82:85], v70 offset:61440
	s_waitcnt lgkmcnt(2)
	v_mfma_f32_32x32x16_bf16 v[50:65], v[78:81], v[74:77], v[50:65]
	v_add_u32_e32 v227, v198, v209
	ds_read_b128 v[78:81], v227 offset:49152
	v_mfma_f32_32x32x16_bf16 v[34:49], v[232:235], v[74:77], v[34:49]
	s_cbranch_scc1 .LBB0_466
	s_cmp_lt_i32 s61, s39
	s_movk_i32 s79, 0xc0
	s_cselect_b32 s79, s79, 0x140
	s_add_i32 s80, s60, s79
	s_ashr_i32 s81, s80, 31
	s_lshl_b64 s[80:81], s[80:81], 12
	s_add_i32 s60, s10, 0xffffc000
	s_cmp_lg_u32 s4, 0
	s_cselect_b32 s60, s60, 0x8000
	v_lshl_add_u64 v[66:67], v[202:203], 0, s[80:81]
	s_add_i32 s60, s7, s60
	v_lshl_add_u64 v[68:69], v[66:67], 0, s[30:31]
	s_mov_b32 m0, s60
	v_lshl_add_u64 v[66:67], v[66:67], 0, s[36:37]
	global_load_lds_dwordx4 v[68:69], off
	s_add_i32 m0, s60, 0x2000
	s_nop 0
	global_load_lds_dwordx4 v[66:67], off
.LBB0_466:
	s_cmp_lt_i32 s78, s39
	s_cselect_b64 s[80:81], -1, 0
	v_cndmask_b32_e64 v228, -v201, v201, s[80:81]
	s_and_b64 s[80:81], s[80:81], exec
	s_cselect_b32 s60, s78, s61
	s_add_i32 s60, s60, s33
	s_lshl_b32 s78, s60, 6
	s_ashr_i32 s79, s78, 31
	s_lshl_b64 s[80:81], s[78:79], 1
	s_addk_i32 s62, 0xc000
	s_cmp_lg_u32 s5, 0
	s_cselect_b32 s60, s62, 0x8000
	s_add_i32 s60, s14, s60
	v_lshl_add_u64 v[66:67], v[204:205], 0, s[80:81]
	s_add_i32 m0, s60, 0xc000
	v_lshl_add_u64 v[68:69], v[206:207], 0, s[80:81]
	global_load_lds_dwordx4 v[66:67], off
	s_add_i32 m0, s60, 0xc400
	v_cvt_f32_i32_e32 v66, s78
	global_load_lds_dwordx4 v[68:69], off
	v_exp_f32_e32 v231, v98
	v_add_f32_e32 v66, v155, v66
	v_fma_f32 v230, v228, v66, -v199
	v_add_u32_e32 v229, s10, v218
	v_exp_f32_e32 v233, v114
	v_fma_f32 v66, 0, v228, v230
	v_exp_f32_e32 v234, v99
	v_exp_f32_e32 v235, v115
	v_add_f32_e32 v67, v228, v230
	v_exp_f32_e32 v236, v100
	v_exp_f32_e32 v237, v116
	v_exp_f32_e32 v238, v101
	v_exp_f32_e32 v239, v117
	v_fma_f32 v68, v228, s64, v230
	v_fma_f32 v69, v228, s65, v230
	v_fma_f32 v70, v228, s66, v230
	v_fma_f32 v71, v228, s67, v230
	v_cvt_pk_bf16_f32 v98, v249, v250
	v_cvt_pk_bf16_f32 v99, v195, v251
	v_cvt_pk_bf16_f32 v100, v252, v253
	v_cvt_pk_bf16_f32 v101, v72, v73
	v_cvt_pk_bf16_f32 v114, v90, v91
	v_cvt_pk_bf16_f32 v115, v92, v93
	v_cvt_pk_bf16_f32 v116, v94, v95
	v_cvt_pk_bf16_f32 v117, v96, v97
	v_mul_f32_e32 v232, 0x42000000, v228
	v_exp_f32_e32 v240, v102
	v_exp_f32_e32 v241, v118
	v_exp_f32_e32 v242, v103
	v_exp_f32_e32 v243, v119
	ds_read_b128 v[90:93], v227 offset:53248
	s_waitcnt lgkmcnt(2)
	v_mfma_f32_32x32x16_bf16 v[18:33], v[86:89], v[74:77], v[18:33]
	v_add_f32_e32 v254, 0, v231
	v_add_f32_e32 v254, v233, v254
	v_fma_f32 v72, v228, s68, v230
	v_fma_f32 v73, v228, s69, v230
	v_exp_f32_e32 v181, v104
	v_exp_f32_e32 v183, v120
	ds_read_b128 v[86:89], v227 offset:57344
	v_mfma_f32_32x32x16_bf16 v[2:17], v[82:85], v[74:77], v[2:17]
	s_setprio 0
	v_add_f32_e32 v254, v234, v254
	v_add_f32_e32 v254, v235, v254
	v_exp_f32_e32 v195, v105
	v_exp_f32_e32 v200, v121
	ds_read_b128 v[82:85], v227 offset:61440
	s_waitcnt lgkmcnt(2)
	v_mfma_f32_32x32x16_bf16 v[50:65], v[78:81], v[98:101], v[50:65]
	v_add_f32_e32 v254, v236, v254
	v_add_f32_e32 v254, v237, v254
	v_fma_f32 v74, v228, s70, v230
	v_fma_f32 v75, v228, s71, v230
	v_exp_f32_e32 v224, v106
	v_exp_f32_e32 v122, v122
	v_add_u32_e32 v78, v198, v226
	ds_read_b128 v[94:97], v78 offset:49152
	v_mfma_f32_32x32x16_bf16 v[34:49], v[90:93], v[98:101], v[34:49]
	v_add_f32_e32 v254, v238, v254
	v_add_f32_e32 v254, v239, v254
	v_exp_f32_e32 v225, v107
	v_exp_f32_e32 v123, v123
	ds_read_b128 v[90:93], v78 offset:53248
	s_waitcnt lgkmcnt(2)
	v_mfma_f32_32x32x16_bf16 v[18:33], v[86:89], v[98:101], v[18:33]
	v_add_f32_e32 v254, v240, v254
	v_add_f32_e32 v254, v241, v254
	v_fma_f32 v76, v228, s72, v230
	v_fma_f32 v77, v228, s73, v230
	v_exp_f32_e32 v227, v108
	v_exp_f32_e32 v124, v124
	ds_read_b128 v[86:89], v78 offset:57344
	v_mfma_f32_32x32x16_bf16 v[2:17], v[82:85], v[98:101], v[2:17]
	v_add_f32_e32 v254, v242, v254
	v_add_f32_e32 v254, v243, v254
	v_exp_f32_e32 v244, v109
	v_exp_f32_e32 v125, v125
	ds_read_b128 v[98:101], v78 offset:61440
	s_waitcnt lgkmcnt(2)
	v_mfma_f32_32x32x16_bf16 v[50:65], v[94:97], v[114:117], v[50:65]
	v_add_f32_e32 v254, v181, v254
	v_add_f32_e32 v254, v183, v254
	v_fma_f32 v78, v228, s74, v230
	v_fma_f32 v79, v228, s75, v230
	v_exp_f32_e32 v245, v110
	v_exp_f32_e32 v126, v126
	v_add_u32_e32 v80, v229, v149
	ds_read_b128 v[102:105], v80
	v_mfma_f32_32x32x16_bf16 v[34:49], v[90:93], v[114:117], v[34:49]
	v_add_f32_e32 v254, v195, v254
	v_add_f32_e32 v254, v200, v254
	v_exp_f32_e32 v246, v111
	v_exp_f32_e32 v127, v127
	ds_read_b128 v[106:109], v80 offset:4096
	s_waitcnt lgkmcnt(2)
	v_mfma_f32_32x32x16_bf16 v[18:33], v[86:89], v[114:117], v[18:33]
	v_add_f32_e32 v254, v224, v254
	v_add_f32_e32 v254, v122, v254
	v_fma_f32 v80, v228, s76, v230
	v_fma_f32 v81, v228, s77, v230
	v_exp_f32_e32 v247, v112
	v_exp_f32_e32 v128, v128
	v_add_u32_e32 v110, v229, v208
	ds_read_b128 v[118:121], v110
	v_mfma_f32_32x32x16_bf16 v[2:17], v[98:101], v[114:117], v[2:17]
	v_add_f32_e32 v254, v225, v254
	v_add_f32_e32 v254, v123, v254
	v_add_f32_e64 v82, v232, v66
	v_add_f32_e64 v83, v232, v67
	v_add_f32_e64 v96, v232, v80
	v_add_f32_e64 v97, v232, v81
	v_add_f32_e64 v94, v232, v78
	v_add_f32_e64 v95, v232, v79
	v_add_f32_e32 v92, v232, v76
	v_add_f32_e32 v93, v232, v77
	v_add_f32_e32 v90, v232, v74
	v_add_f32_e32 v91, v232, v75
	v_add_f32_e32 v88, v232, v72
	v_add_f32_e32 v89, v232, v73
	v_add_f32_e32 v86, v232, v70
	v_add_f32_e32 v87, v232, v71
	v_add_f32_e32 v84, v232, v68
	v_add_f32_e32 v85, v232, v69
	v_exp_f32_e32 v228, v113
	v_exp_f32_e32 v129, v129
	ds_read_b128 v[98:101], v110 offset:4096
	s_waitcnt lgkmcnt(2)
	v_mfma_f32_32x32x16_bf16 v[66:81], v[102:105], v[130:133], v[66:81]
	v_add_f32_e32 v254, v227, v254
	v_add_f32_e32 v254, v124, v254
	v_add_f32_e32 v254, v244, v254
	v_add_u32_e32 v110, v229, v209
	ds_read_b128 v[102:105], v110
	v_mfma_f32_32x32x16_bf16 v[82:97], v[106:109], v[130:133], v[82:97]
	v_add_f32_e32 v254, v125, v254
	v_add_f32_e32 v254, v245, v254
	v_add_f32_e32 v254, v126, v254
	ds_read_b128 v[106:109], v110 offset:4096
	s_waitcnt lgkmcnt(2)
	v_mfma_f32_32x32x16_bf16 v[66:81], v[118:121], v[134:137], v[66:81]
	v_add_f32_e32 v254, v246, v254
	v_add_f32_e32 v254, v127, v254
	v_add_f32_e32 v254, v247, v254
	v_add_u32_e32 v114, v229, v226
	ds_read_b128 v[110:113], v114
	v_mfma_f32_32x32x16_bf16 v[82:97], v[98:101], v[134:137], v[82:97]
	v_add_f32_e32 v254, v128, v254
	v_add_f32_e32 v254, v228, v254
	v_add_f32_e32 v254, v129, v254
	ds_read_b128 v[98:101], v114 offset:4096
	s_waitcnt lgkmcnt(2)
	v_mfma_f32_32x32x16_bf16 v[66:81], v[102:105], v[138:141], v[66:81]
	v_cvt_pk_bf16_f32 v114, v122, v123
	v_cvt_pk_bf16_f32 v115, v124, v125
	v_cvt_pk_bf16_f32 v116, v126, v127
	v_cvt_pk_bf16_f32 v117, v128, v129
	v_mfma_f32_32x32x16_bf16 v[82:97], v[106:109], v[138:141], v[82:97]
	v_cvt_pk_bf16_f32 v106, v224, v225
	v_cvt_pk_bf16_f32 v107, v227, v244
	v_cvt_pk_bf16_f32 v108, v245, v246
	v_cvt_pk_bf16_f32 v109, v247, v228
	s_waitcnt lgkmcnt(0)
	v_mfma_f32_32x32x16_bf16 v[66:81], v[110:113], v[142:145], v[66:81]
	v_cvt_pk_bf16_f32 v110, v233, v235
	v_cvt_pk_bf16_f32 v111, v237, v239
	v_cvt_pk_bf16_f32 v112, v241, v243
	v_cvt_pk_bf16_f32 v113, v183, v200
	v_mfma_f32_32x32x16_bf16 v[82:97], v[98:101], v[142:145], v[82:97]
	s_add_i32 s10, s4, 1
	s_cmp_lg_u32 s4, 2
	s_cselect_b32 s62, s10, 0
	s_add_i32 s4, s5, 1
	s_cmp_lg_u32 s5, 2
	s_cselect_b32 s10, s4, 0
	s_add_i32 s34, s34, 2
	v_add_f32_e32 v198, v179, v254
	v_cvt_pk_bf16_f32 v98, v231, v234
	v_cvt_pk_bf16_f32 v99, v236, v238
	v_cvt_pk_bf16_f32 v100, v240, v242
	v_cvt_pk_bf16_f32 v101, v181, v195
	s_cmp_ge_i32 s61, s48
	s_cbranch_scc1 .LBB0_473
	s_mov_b32 s60, s63
	s_add_i32 s61, s34, -2
	s_cmp_gt_i32 s61, s48
	s_mov_b64 s[4:5], -1
	s_cbranch_scc1 .LBB0_451
